# weight transposes: both 16-row load batches of a block issued back to back (one memory round trip per block instead of two)
# speedup vs baseline: 1.0058x; 1.0056x over previous
; #define LDS_WAIT() asm volatile("s_waitcnt lgkmcnt(0)" ::: "memory")
; __device__ __forceinline__ void transpose_mat(const float* __restrict__ W, int K, int N, int Npad, bf16_t* __restrict__ WT, int blk_mul, int blk_off,
;                                               LAS float* scr, int gw, int NGW, int lane, const float* __restrict__ gk = nullptr) {
;     ...
;     for (int it = gw; it < nitems; it += NGW) {
;         const int kb = it / nblk, nb = it % nblk, k0 = 64 * kb, n0 = 32 * nb;
;         const int ncol = n0 + (lane & 31);
; #pragma unroll
;         for (int i = 0; i < 32; ++i) { const int kk = 2 * i + (lane >> 5); float w = (ncol < N) ? W[(size_t)(k0 + kk) * N + ncol] : 0.f; if (gk) w *= gk[k0 + kk]; scr[kk * 33 + (lane & 31)] = w; }
;         LDS_WAIT();
.LBB0_71:
	v_mov_b32_e32 v152, 0
	s_and_saveexec_b64 s[54:55], s[2:3]
	s_cbranch_execz .LBB0_73
	v_or_b32_e32 v14, s52, v35
	v_mad_i64_i32 v[14:15], s[70:71], v14, s60, v[12:13]
	global_load_dword v152, v[14:15], off

; #define LDS_WAIT() asm volatile("s_waitcnt lgkmcnt(0)" ::: "memory")
; __device__ __forceinline__ void transpose_mat(const float* __restrict__ W, int K, int N, int Npad, bf16_t* __restrict__ WT, int blk_mul, int blk_off,
;                                               LAS float* scr, int gw, int NGW, int lane, const float* __restrict__ gk = nullptr) {
;     ...
;         for (int i = 0; i < 32; ++i) { const int kk = 2 * i + (lane >> 5); float w = (ncol < N) ? W[(size_t)(k0 + kk) * N + ncol] : 0.f; if (gk) w *= gk[k0 + kk]; scr[kk * 33 + (lane & 31)] = w; }
;         LDS_WAIT();
.LBB0_135:
.LBB0_136:
	s_ashr_i32 s53, s52, 31
	v_mov_b32_e32 v12, v15
	s_waitcnt vmcnt(0)
	s_and_b64 vcc, exec, s[40:41]
	s_cbranch_vccz .Ltp0_nomul_1
	v_mul_f32_e32 v136, v136, v168
	v_mul_f32_e32 v137, v137, v169
	v_mul_f32_e32 v138, v138, v170
	v_mul_f32_e32 v139, v139, v171
	v_mul_f32_e32 v140, v140, v172
	v_mul_f32_e32 v141, v141, v173
	v_mul_f32_e32 v142, v142, v174
	v_mul_f32_e32 v143, v143, v175
	v_mul_f32_e32 v144, v144, v176
	v_mul_f32_e32 v145, v145, v177
	v_mul_f32_e32 v146, v146, v178
	v_mul_f32_e32 v147, v147, v179
	v_mul_f32_e32 v148, v148, v180
	v_mul_f32_e32 v149, v149, v181
	v_mul_f32_e32 v150, v150, v182
	v_mul_f32_e32 v151, v151, v183
.Ltp0_nomul_1:
	v_add_u32_e32 v14, v51, v5
	ds_write_b32 v14, v136
	v_add_u32_e32 v15, v51, v69
	ds_write_b32 v15, v137
	v_add_u32_e32 v15, v51, v70
	ds_write_b32 v15, v138
	v_add_u32_e32 v15, v51, v71
	ds_write_b32 v15, v139
	v_add_u32_e32 v15, v51, v68
	ds_write_b32 v15, v140
	v_add_u32_e32 v15, v51, v72
	ds_write_b32 v15, v141
	v_add_u32_e32 v15, v51, v73
	ds_write_b32 v15, v142
	v_add_u32_e32 v15, v51, v74
	ds_write_b32 v15, v143
	v_add_u32_e32 v15, v51, v78
	ds_write_b32 v15, v144
	v_add_u32_e32 v15, v51, v75
	ds_write_b32 v15, v145
	v_add_u32_e32 v15, v51, v76
	ds_write_b32 v15, v146
	v_add_u32_e32 v15, v51, v77
	ds_write_b32 v15, v147
	v_add_u32_e32 v15, v51, v55
	ds_write_b32 v15, v148
	v_add_u32_e32 v15, v51, v57
	ds_write_b32 v15, v149
	v_add_u32_e32 v15, v51, v58
	ds_write_b32 v15, v150
	v_add_u32_e32 v15, v51, v59
	ds_write_b32 v15, v151
	s_waitcnt vmcnt(0)
	s_and_b64 vcc, exec, s[40:41]
	s_cbranch_vccz .Ltp0_nomul_2
	v_mul_f32_e32 v152, v152, v184
	v_mul_f32_e32 v153, v153, v185
	v_mul_f32_e32 v154, v154, v186
	v_mul_f32_e32 v155, v155, v187
	v_mul_f32_e32 v156, v156, v188
	v_mul_f32_e32 v157, v157, v189
	v_mul_f32_e32 v158, v158, v190
	v_mul_f32_e32 v159, v159, v191
	v_mul_f32_e32 v160, v160, v192
	v_mul_f32_e32 v161, v161, v193
	v_mul_f32_e32 v162, v162, v194
	v_mul_f32_e32 v163, v163, v195
	v_mul_f32_e32 v164, v164, v196
	v_mul_f32_e32 v165, v165, v197
	v_mul_f32_e32 v166, v166, v198
	v_mul_f32_e32 v167, v167, v199

; #define LDS_WAIT() asm volatile("s_waitcnt lgkmcnt(0)" ::: "memory")
; __device__ __forceinline__ void transpose_mat(const float* __restrict__ W, int K, int N, int Npad, bf16_t* __restrict__ WT, int blk_mul, int blk_off,
;                                               LAS float* scr, int gw, int NGW, int lane, const float* __restrict__ gk = nullptr) {
;     ...
;     for (int it = gw; it < nitems; it += NGW) {
;         const int kb = it / nblk, nb = it % nblk, k0 = 64 * kb, n0 = 32 * nb;
;         const int ncol = n0 + (lane & 31);
; #pragma unroll
;         for (int i = 0; i < 32; ++i) { const int kk = 2 * i + (lane >> 5); float w = (ncol < N) ? W[(size_t)(k0 + kk) * N + ncol] : 0.f; if (gk) w *= gk[k0 + kk]; scr[kk * 33 + (lane & 31)] = w; }
;         LDS_WAIT();
.LBB0_206:
	v_mov_b32_e32 v152, 0
	s_and_saveexec_b64 s[54:55], s[2:3]
	s_cbranch_execz .LBB0_208
	v_or_b32_e32 v83, s48, v35
	v_mad_i64_i32 v[84:85], s[68:69], v83, s60, v[12:13]
	global_load_dword v152, v[84:85], off

; #define LDS_WAIT() asm volatile("s_waitcnt lgkmcnt(0)" ::: "memory")
; __device__ __forceinline__ void transpose_mat(const float* __restrict__ W, int K, int N, int Npad, bf16_t* __restrict__ WT, int blk_mul, int blk_off,
;                                               LAS float* scr, int gw, int NGW, int lane, const float* __restrict__ gk = nullptr) {
;     ...
;         for (int i = 0; i < 32; ++i) { const int kk = 2 * i + (lane >> 5); float w = (ncol < N) ? W[(size_t)(k0 + kk) * N + ncol] : 0.f; if (gk) w *= gk[k0 + kk]; scr[kk * 33 + (lane & 31)] = w; }
;         LDS_WAIT();
.LBB0_270:
.LBB0_271:
	s_ashr_i32 s49, s48, 31
	v_mov_b32_e32 v12, v87
	s_waitcnt vmcnt(0)
	s_and_b64 vcc, exec, s[40:41]
	s_cbranch_vccz .Ltp1_nomul_1
	v_mul_f32_e32 v136, v136, v168
	v_mul_f32_e32 v137, v137, v169
	v_mul_f32_e32 v138, v138, v170
	v_mul_f32_e32 v139, v139, v171
	v_mul_f32_e32 v140, v140, v172
	v_mul_f32_e32 v141, v141, v173
	v_mul_f32_e32 v142, v142, v174
	v_mul_f32_e32 v143, v143, v175
	v_mul_f32_e32 v144, v144, v176
	v_mul_f32_e32 v145, v145, v177
	v_mul_f32_e32 v146, v146, v178
	v_mul_f32_e32 v147, v147, v179
	v_mul_f32_e32 v148, v148, v180
	v_mul_f32_e32 v149, v149, v181
	v_mul_f32_e32 v150, v150, v182
	v_mul_f32_e32 v151, v151, v183
.Ltp1_nomul_1:
	v_add_u32_e32 v6, v51, v5
	ds_write_b32 v6, v136
	v_add_u32_e32 v15, v51, v69
	ds_write_b32 v15, v137
	v_add_u32_e32 v15, v51, v70
	ds_write_b32 v15, v138
	v_add_u32_e32 v15, v51, v71
	ds_write_b32 v15, v139
	v_add_u32_e32 v14, v51, v68
	ds_write_b32 v14, v140
	v_add_u32_e32 v80, v51, v72
	ds_write_b32 v80, v141
	v_add_u32_e32 v80, v51, v73
	ds_write_b32 v80, v142
	v_add_u32_e32 v80, v51, v74
	ds_write_b32 v80, v143
	v_add_u32_e32 v15, v51, v78
	ds_write_b32 v15, v144
	v_add_u32_e32 v83, v51, v75
	ds_write_b32 v83, v145
	v_add_u32_e32 v83, v51, v76
	ds_write_b32 v83, v146
	v_add_u32_e32 v83, v51, v77
	ds_write_b32 v83, v147
	v_add_u32_e32 v80, v51, v55
	ds_write_b32 v80, v148
	v_add_u32_e32 v84, v51, v57
	ds_write_b32 v84, v149
	v_add_u32_e32 v84, v51, v58
	ds_write_b32 v84, v150
	v_add_u32_e32 v84, v51, v59
	ds_write_b32 v84, v151
	s_waitcnt vmcnt(0)
	s_and_b64 vcc, exec, s[40:41]
	s_cbranch_vccz .Ltp1_nomul_2
	v_mul_f32_e32 v152, v152, v184
	v_mul_f32_e32 v153, v153, v185
	v_mul_f32_e32 v154, v154, v186
	v_mul_f32_e32 v155, v155, v187
	v_mul_f32_e32 v156, v156, v188
	v_mul_f32_e32 v157, v157, v189
	v_mul_f32_e32 v158, v158, v190
	v_mul_f32_e32 v159, v159, v191
	v_mul_f32_e32 v160, v160, v192
	v_mul_f32_e32 v161, v161, v193
	v_mul_f32_e32 v162, v162, v194
	v_mul_f32_e32 v163, v163, v195
	v_mul_f32_e32 v164, v164, v196
	v_mul_f32_e32 v165, v165, v197
	v_mul_f32_e32 v166, v166, v198
	v_mul_f32_e32 v167, v167, v199

; #define LDS_WAIT() asm volatile("s_waitcnt lgkmcnt(0)" ::: "memory")
; __device__ __forceinline__ void transpose_mat(const float* __restrict__ W, int K, int N, int Npad, bf16_t* __restrict__ WT, int blk_mul, int blk_off,
;                                               LAS float* scr, int gw, int NGW, int lane, const float* __restrict__ gk = nullptr) {
;     ...
;     for (int it = gw; it < nitems; it += NGW) {
;         const int kb = it / nblk, nb = it % nblk, k0 = 64 * kb, n0 = 32 * nb;
;         const int ncol = n0 + (lane & 31);
; #pragma unroll
;         for (int i = 0; i < 32; ++i) { const int kk = 2 * i + (lane >> 5); float w = (ncol < N) ? W[(size_t)(k0 + kk) * N + ncol] : 0.f; if (gk) w *= gk[k0 + kk]; scr[kk * 33 + (lane & 31)] = w; }
;         LDS_WAIT();
.LBB0_357:
	v_mov_b32_e32 v152, 0
	s_and_saveexec_b64 s[12:13], s[4:5]
	s_cbranch_execz .LBB0_359
	v_or_b32_e32 v10, s10, v35
	v_mad_i64_i32 v[10:11], s[36:37], v10, s33, v[8:9]
	global_load_dword v152, v[10:11], off

; #define LDS_WAIT() asm volatile("s_waitcnt lgkmcnt(0)" ::: "memory")
; __device__ __forceinline__ void transpose_mat(const float* __restrict__ W, int K, int N, int Npad, bf16_t* __restrict__ WT, int blk_mul, int blk_off,
;                                               LAS float* scr, int gw, int NGW, int lane, const float* __restrict__ gk = nullptr) {
;     ...
;         for (int i = 0; i < 32; ++i) { const int kk = 2 * i + (lane >> 5); float w = (ncol < N) ? W[(size_t)(k0 + kk) * N + ncol] : 0.f; if (gk) w *= gk[k0 + kk]; scr[kk * 33 + (lane & 31)] = w; }
;         LDS_WAIT();
.LBB0_421:
.LBB0_422:
	s_ashr_i32 s11, s10, 31
	v_mov_b32_e32 v8, v11
	s_waitcnt vmcnt(0)
	s_and_b64 vcc, exec, s[8:9]
	s_cbranch_vccz .Ltp2_nomul_1
	v_mul_f32_e32 v136, v136, v168
	v_mul_f32_e32 v137, v137, v169
	v_mul_f32_e32 v138, v138, v170
	v_mul_f32_e32 v139, v139, v171
	v_mul_f32_e32 v140, v140, v172
	v_mul_f32_e32 v141, v141, v173
	v_mul_f32_e32 v142, v142, v174
	v_mul_f32_e32 v143, v143, v175
	v_mul_f32_e32 v144, v144, v176
	v_mul_f32_e32 v145, v145, v177
	v_mul_f32_e32 v146, v146, v178
	v_mul_f32_e32 v147, v147, v179
	v_mul_f32_e32 v148, v148, v180
	v_mul_f32_e32 v149, v149, v181
	v_mul_f32_e32 v150, v150, v182
	v_mul_f32_e32 v151, v151, v183
.Ltp2_nomul_1:
	ds_write_b32 v14, v136
	ds_write_b32 v5, v137
	ds_write_b32 v12, v138
	ds_write_b32 v13, v139
	ds_write_b32 v15, v140
	ds_write_b32 v69, v141
	ds_write_b32 v70, v142
	ds_write_b32 v71, v143
	ds_write_b32 v68, v144
	ds_write_b32 v72, v145
	ds_write_b32 v73, v146
	ds_write_b32 v74, v147
	v_add_u32_e32 v11, v51, v55
	ds_write_b32 v11, v148
	v_add_u32_e32 v11, v51, v57
	ds_write_b32 v11, v149
	v_add_u32_e32 v11, v51, v58
	ds_write_b32 v11, v150
	v_add_u32_e32 v11, v51, v59
	ds_write_b32 v11, v151
	s_waitcnt vmcnt(0)
	s_and_b64 vcc, exec, s[8:9]
	s_cbranch_vccz .Ltp2_nomul_2
	v_mul_f32_e32 v152, v152, v184
	v_mul_f32_e32 v153, v153, v185
	v_mul_f32_e32 v154, v154, v186
	v_mul_f32_e32 v155, v155, v187
	v_mul_f32_e32 v156, v156, v188
	v_mul_f32_e32 v157, v157, v189
	v_mul_f32_e32 v158, v158, v190
	v_mul_f32_e32 v159, v159, v191
	v_mul_f32_e32 v160, v160, v192
	v_mul_f32_e32 v161, v161, v193
	v_mul_f32_e32 v162, v162, v194
	v_mul_f32_e32 v163, v163, v195
	v_mul_f32_e32 v164, v164, v196
	v_mul_f32_e32 v165, v165, v197
	v_mul_f32_e32 v166, v166, v198
	v_mul_f32_e32 v167, v167, v199

; #define LDS_WAIT() asm volatile("s_waitcnt lgkmcnt(0)" ::: "memory")
; __device__ __forceinline__ void transpose_mat(const float* __restrict__ W, int K, int N, int Npad, bf16_t* __restrict__ WT, int blk_mul, int blk_off,
;                                               LAS float* scr, int gw, int NGW, int lane, const float* __restrict__ gk = nullptr) {
;     ...
;     for (int it = gw; it < nitems; it += NGW) {
;         const int kb = it / nblk, nb = it % nblk, k0 = 64 * kb, n0 = 32 * nb;
;         const int ncol = n0 + (lane & 31);
; #pragma unroll
;         for (int i = 0; i < 32; ++i) { const int kk = 2 * i + (lane >> 5); float w = (ncol < N) ? W[(size_t)(k0 + kk) * N + ncol] : 0.f; if (gk) w *= gk[k0 + kk]; scr[kk * 33 + (lane & 31)] = w; }
;         LDS_WAIT();
.LBB0_2515:
	v_mov_b32_e32 v152, 0
	s_and_saveexec_b64 s[20:21], s[4:5]
	s_cbranch_execz .LBB0_2517
	v_or_b32_e32 v36, s18, v59
	v_mad_i64_i32 v[36:37], s[30:31], v36, s70, v[34:35]
	global_load_dword v152, v[36:37], off

; #define LDS_WAIT() asm volatile("s_waitcnt lgkmcnt(0)" ::: "memory")
; __device__ __forceinline__ void transpose_mat(const float* __restrict__ W, int K, int N, int Npad, bf16_t* __restrict__ WT, int blk_mul, int blk_off,
;                                               LAS float* scr, int gw, int NGW, int lane, const float* __restrict__ gk = nullptr) {
;     ...
;         for (int i = 0; i < 32; ++i) { const int kk = 2 * i + (lane >> 5); float w = (ncol < N) ? W[(size_t)(k0 + kk) * N + ncol] : 0.f; if (gk) w *= gk[k0 + kk]; scr[kk * 33 + (lane & 31)] = w; }
;         LDS_WAIT();
.LBB0_2579:
.LBB0_2580:
	s_ashr_i32 s19, s18, 31
	v_mov_b32_e32 v34, v37
	s_waitcnt vmcnt(0)
	s_and_b64 vcc, exec, s[2:3]
	s_cbranch_vccz .Ltp3_nomul_1
	v_mul_f32_e32 v136, v136, v168
	v_mul_f32_e32 v137, v137, v169
	v_mul_f32_e32 v138, v138, v170
	v_mul_f32_e32 v139, v139, v171
	v_mul_f32_e32 v140, v140, v172
	v_mul_f32_e32 v141, v141, v173
	v_mul_f32_e32 v142, v142, v174
	v_mul_f32_e32 v143, v143, v175
	v_mul_f32_e32 v144, v144, v176
	v_mul_f32_e32 v145, v145, v177
	v_mul_f32_e32 v146, v146, v178
	v_mul_f32_e32 v147, v147, v179
	v_mul_f32_e32 v148, v148, v180
	v_mul_f32_e32 v149, v149, v181
	v_mul_f32_e32 v150, v150, v182
	v_mul_f32_e32 v151, v151, v183
.Ltp3_nomul_1:
	v_add_u32_e32 v36, v39, v40
	ds_write_b32 v36, v136
	v_add_u32_e32 v37, v39, v80
	ds_write_b32 v37, v137
	v_add_u32_e32 v37, v39, v81
	ds_write_b32 v37, v138
	v_add_u32_e32 v37, v39, v82
	ds_write_b32 v37, v139
	v_add_u32_e32 v37, v39, v45
	ds_write_b32 v37, v140
	v_add_u32_e32 v37, v39, v83
	ds_write_b32 v37, v141
	v_add_u32_e32 v37, v39, v84
	ds_write_b32 v37, v142
	v_add_u32_e32 v37, v39, v85
	ds_write_b32 v37, v143
	v_add_u32_e32 v37, v39, v50
	ds_write_b32 v37, v144
	v_add_u32_e32 v37, v39, v86
	ds_write_b32 v37, v145
	v_add_u32_e32 v37, v39, v87
	ds_write_b32 v37, v146
	v_add_u32_e32 v37, v39, v88
	ds_write_b32 v37, v147
	v_add_u32_e32 v37, v39, v55
	ds_write_b32 v37, v148
	v_add_u32_e32 v37, v39, v89
	ds_write_b32 v37, v149
	v_add_u32_e32 v37, v39, v90
	ds_write_b32 v37, v150
	v_add_u32_e32 v37, v39, v91
	ds_write_b32 v37, v151
	s_waitcnt vmcnt(0)
	s_and_b64 vcc, exec, s[2:3]
	s_cbranch_vccz .Ltp3_nomul_2
	v_mul_f32_e32 v152, v152, v184
	v_mul_f32_e32 v153, v153, v185
	v_mul_f32_e32 v154, v154, v186
	v_mul_f32_e32 v155, v155, v187
	v_mul_f32_e32 v156, v156, v188
	v_mul_f32_e32 v157, v157, v189
	v_mul_f32_e32 v158, v158, v190
	v_mul_f32_e32 v159, v159, v191
	v_mul_f32_e32 v160, v160, v192
	v_mul_f32_e32 v161, v161, v193
	v_mul_f32_e32 v162, v162, v194
	v_mul_f32_e32 v163, v163, v195
	v_mul_f32_e32 v164, v164, v196
	v_mul_f32_e32 v165, v165, v197
	v_mul_f32_e32 v166, v166, v198
	v_mul_f32_e32 v167, v167, v199

; #define LDS_WAIT() asm volatile("s_waitcnt lgkmcnt(0)" ::: "memory")
; __device__ __forceinline__ void transpose_mat(const float* __restrict__ W, int K, int N, int Npad, bf16_t* __restrict__ WT, int blk_mul, int blk_off,
;                                               LAS float* scr, int gw, int NGW, int lane, const float* __restrict__ gk = nullptr) {
;     ...
;     for (int it = gw; it < nitems; it += NGW) {
;         const int kb = it / nblk, nb = it % nblk, k0 = 64 * kb, n0 = 32 * nb;
;         const int ncol = n0 + (lane & 31);
; #pragma unroll
;         for (int i = 0; i < 32; ++i) { const int kk = 2 * i + (lane >> 5); float w = (ncol < N) ? W[(size_t)(k0 + kk) * N + ncol] : 0.f; if (gk) w *= gk[k0 + kk]; scr[kk * 33 + (lane & 31)] = w; }
;         LDS_WAIT();
.LBB0_2650:
	v_mov_b32_e32 v152, 0
	s_and_saveexec_b64 s[20:21], s[4:5]
	s_cbranch_execz .LBB0_2652
	v_or_b32_e32 v102, s16, v59
	v_mad_i64_i32 v[102:103], s[30:31], v102, s70, v[34:35]
	global_load_dword v152, v[102:103], off

; #define LDS_WAIT() asm volatile("s_waitcnt lgkmcnt(0)" ::: "memory")
; __device__ __forceinline__ void transpose_mat(const float* __restrict__ W, int K, int N, int Npad, bf16_t* __restrict__ WT, int blk_mul, int blk_off,
;                                               LAS float* scr, int gw, int NGW, int lane, const float* __restrict__ gk = nullptr) {
;     ...
;         for (int i = 0; i < 32; ++i) { const int kk = 2 * i + (lane >> 5); float w = (ncol < N) ? W[(size_t)(k0 + kk) * N + ncol] : 0.f; if (gk) w *= gk[k0 + kk]; scr[kk * 33 + (lane & 31)] = w; }
;         LDS_WAIT();
.LBB0_2714:
.LBB0_2715:
	s_ashr_i32 s17, s16, 31
	v_mov_b32_e32 v34, v108
	s_waitcnt vmcnt(0)
	s_and_b64 vcc, exec, s[2:3]
	s_cbranch_vccz .Ltp4_nomul_1
	v_mul_f32_e32 v136, v136, v168
	v_mul_f32_e32 v137, v137, v169
	v_mul_f32_e32 v138, v138, v170
	v_mul_f32_e32 v139, v139, v171
	v_mul_f32_e32 v140, v140, v172
	v_mul_f32_e32 v141, v141, v173
	v_mul_f32_e32 v142, v142, v174
	v_mul_f32_e32 v143, v143, v175
	v_mul_f32_e32 v144, v144, v176
	v_mul_f32_e32 v145, v145, v177
	v_mul_f32_e32 v146, v146, v178
	v_mul_f32_e32 v147, v147, v179
	v_mul_f32_e32 v148, v148, v180
	v_mul_f32_e32 v149, v149, v181
	v_mul_f32_e32 v150, v150, v182
	v_mul_f32_e32 v151, v151, v183
.Ltp4_nomul_1:
	v_add_u32_e32 v36, v39, v40
	ds_write_b32 v36, v136
	v_add_u32_e32 v100, v39, v80
	ds_write_b32 v100, v137
	v_add_u32_e32 v100, v39, v81
	ds_write_b32 v100, v138
	v_add_u32_e32 v100, v39, v82
	ds_write_b32 v100, v139
	v_add_u32_e32 v37, v39, v45
	ds_write_b32 v37, v140
	v_add_u32_e32 v101, v39, v83
	ds_write_b32 v101, v141
	v_add_u32_e32 v101, v39, v84
	ds_write_b32 v101, v142
	v_add_u32_e32 v101, v39, v85
	ds_write_b32 v101, v143
	v_add_u32_e32 v100, v39, v50
	ds_write_b32 v100, v144
	v_add_u32_e32 v102, v39, v86
	ds_write_b32 v102, v145
	v_add_u32_e32 v102, v39, v87
	ds_write_b32 v102, v146
	v_add_u32_e32 v102, v39, v88
	ds_write_b32 v102, v147
	v_add_u32_e32 v101, v39, v55
	ds_write_b32 v101, v148
	v_add_u32_e32 v103, v39, v89
	ds_write_b32 v103, v149
	v_add_u32_e32 v103, v39, v90
	ds_write_b32 v103, v150
	v_add_u32_e32 v103, v39, v91
	ds_write_b32 v103, v151
	s_waitcnt vmcnt(0)
	s_and_b64 vcc, exec, s[2:3]
	s_cbranch_vccz .Ltp4_nomul_2
	v_mul_f32_e32 v152, v152, v184
	v_mul_f32_e32 v153, v153, v185
	v_mul_f32_e32 v154, v154, v186
	v_mul_f32_e32 v155, v155, v187
	v_mul_f32_e32 v156, v156, v188
	v_mul_f32_e32 v157, v157, v189
	v_mul_f32_e32 v158, v158, v190
	v_mul_f32_e32 v159, v159, v191
	v_mul_f32_e32 v160, v160, v192
	v_mul_f32_e32 v161, v161, v193
	v_mul_f32_e32 v162, v162, v194
	v_mul_f32_e32 v163, v163, v195
	v_mul_f32_e32 v164, v164, v196
	v_mul_f32_e32 v165, v165, v197
	v_mul_f32_e32 v166, v166, v198
	v_mul_f32_e32 v167, v167, v199

; #define LDS_WAIT() asm volatile("s_waitcnt lgkmcnt(0)" ::: "memory")
; __device__ __forceinline__ void transpose_mat(const float* __restrict__ W, int K, int N, int Npad, bf16_t* __restrict__ WT, int blk_mul, int blk_off,
;                                               LAS float* scr, int gw, int NGW, int lane, const float* __restrict__ gk = nullptr) {
;     ...
;     for (int it = gw; it < nitems; it += NGW) {
;         const int kb = it / nblk, nb = it % nblk, k0 = 64 * kb, n0 = 32 * nb;
;         const int ncol = n0 + (lane & 31);
; #pragma unroll
;         for (int i = 0; i < 32; ++i) { const int kk = 2 * i + (lane >> 5); float w = (ncol < N) ? W[(size_t)(k0 + kk) * N + ncol] : 0.f; if (gk) w *= gk[k0 + kk]; scr[kk * 33 + (lane & 31)] = w; }
;         LDS_WAIT();
.LBB0_2801:
	v_mov_b32_e32 v152, 0
	v_or_b32_e32 v8, s8, v59
	s_and_saveexec_b64 s[10:11], s[4:5]
	s_cbranch_execz .LBB0_2803
	s_movk_i32 s9, 0x26e0
	v_mad_i64_i32 v[10:11], s[16:17], v8, s9, v[6:7]
	global_load_dword v152, v[10:11], off

; #define LDS_WAIT() asm volatile("s_waitcnt lgkmcnt(0)" ::: "memory")
; __device__ __forceinline__ void transpose_mat(const float* __restrict__ W, int K, int N, int Npad, bf16_t* __restrict__ WT, int blk_mul, int blk_off,
;                                               LAS float* scr, int gw, int NGW, int lane, const float* __restrict__ gk = nullptr) {
;     ...
;         for (int i = 0; i < 32; ++i) { const int kk = 2 * i + (lane >> 5); float w = (ncol < N) ? W[(size_t)(k0 + kk) * N + ncol] : 0.f; if (gk) w *= gk[k0 + kk]; scr[kk * 33 + (lane & 31)] = w; }
;         LDS_WAIT();
.LBB0_2863:
	s_or_b64 exec, exec, s[10:11]
	s_and_b64 vcc, exec, s[6:7]
	s_cbranch_vccnz .Ltp5_join
	v_ashrrev_i32_e32 v9, 31, v8
	v_lshl_add_u64 v[6:7], v[8:9], 2, v[2:3]
	global_load_dword v199, v[6:7], off
.Ltp5_join:
	s_waitcnt vmcnt(0)
	s_and_b64 vcc, exec, s[6:7]
	s_cbranch_vccnz .Ltp5_nomul_1
	v_mul_f32_e32 v136, v136, v168
	v_mul_f32_e32 v137, v137, v169
	v_mul_f32_e32 v138, v138, v170
	v_mul_f32_e32 v139, v139, v171
	v_mul_f32_e32 v140, v140, v172
	v_mul_f32_e32 v141, v141, v173
	v_mul_f32_e32 v142, v142, v174
	v_mul_f32_e32 v143, v143, v175
	v_mul_f32_e32 v144, v144, v176
	v_mul_f32_e32 v145, v145, v177
	v_mul_f32_e32 v146, v146, v178
	v_mul_f32_e32 v147, v147, v179
	v_mul_f32_e32 v148, v148, v180
	v_mul_f32_e32 v149, v149, v181
	v_mul_f32_e32 v150, v150, v182
	v_mul_f32_e32 v151, v151, v183
.Ltp5_nomul_1:
	v_add_u32_e32 v8, v39, v40
	ds_write_b32 v8, v136
	v_add_u32_e32 v8, v39, v80
	ds_write_b32 v8, v137
	v_add_u32_e32 v8, v39, v81
	ds_write_b32 v8, v138
	v_add_u32_e32 v8, v39, v82
	ds_write_b32 v8, v139
	v_add_u32_e32 v8, v39, v45
	ds_write_b32 v8, v140
	v_add_u32_e32 v8, v39, v83
	ds_write_b32 v8, v141
	v_add_u32_e32 v8, v39, v84
	ds_write_b32 v8, v142
	v_add_u32_e32 v8, v39, v85
	ds_write_b32 v8, v143
	v_add_u32_e32 v8, v39, v50
	ds_write_b32 v8, v144
	v_add_u32_e32 v8, v39, v86
	ds_write_b32 v8, v145
	v_add_u32_e32 v8, v39, v87
	ds_write_b32 v8, v146
	v_add_u32_e32 v8, v39, v88
	ds_write_b32 v8, v147
	v_add_u32_e32 v8, v39, v55
	ds_write_b32 v8, v148
	v_add_u32_e32 v8, v39, v89
	ds_write_b32 v8, v149
	v_add_u32_e32 v8, v39, v90
	ds_write_b32 v8, v150
	v_add_u32_e32 v8, v39, v91
	ds_write_b32 v8, v151
	s_waitcnt vmcnt(0)
	s_and_b64 vcc, exec, s[6:7]
	s_cbranch_vccnz .Ltp5_nomul_2
	v_mul_f32_e32 v152, v152, v184
	v_mul_f32_e32 v153, v153, v185
	v_mul_f32_e32 v154, v154, v186
	v_mul_f32_e32 v155, v155, v187
	v_mul_f32_e32 v156, v156, v188
	v_mul_f32_e32 v157, v157, v189
	v_mul_f32_e32 v158, v158, v190
	v_mul_f32_e32 v159, v159, v191
	v_mul_f32_e32 v160, v160, v192
	v_mul_f32_e32 v161, v161, v193
	v_mul_f32_e32 v162, v162, v194
	v_mul_f32_e32 v163, v163, v195
	v_mul_f32_e32 v164, v164, v196
	v_mul_f32_e32 v165, v165, v197
	v_mul_f32_e32 v166, v166, v198
	v_mul_f32_e32 v167, v167, v199
